# attention: removed dead zero-fill of K/V staging registers (mask is all ones), vmcnt ladder -> one wait, 0+x add
# baseline (speedup 1.0000x reference)
; #define LAS __attribute__((address_space(3)))
; __device__ __forceinline__ void attn_phase(const Params& p, LAS unsigned char* lds) {
;     ...
;             const int tq = qblk * 256 + wid * 32 + c;
;             const size_t rowq = (size_t)b * SEQ + tq;
;             bf16x8 qf[12];
; #pragma unroll
;             for (int d = 0; d < 8; ++d) qf[d] = *(const bf16x8*)(QN + rowq * 1024 + h * 128 + d * 16 + hi * 8);
; #pragma unroll
;             for (int d = 0; d < 4; ++d) qf[8 + d] = *(const bf16x8*)(QR + rowq * 512 + h * 64 + d * 16 + hi * 8);
;             float mrun = -1e30f, lrun = 0.f; f32x16 o[4];
; #pragma unroll
;             for (int d = 0; d < 4; ++d) o[d] = (f32x16){};
;             const int ntiles = 4 * qblk + 5;
;             u32x4 kreg[3], vreg[2];
;     ...
;             LOAD_TILE(0);
;             for (int jt = 0; jt < ntiles; ++jt) {
;                 LAS unsigned char* Ks = lds + (jt & 1) * ABUF; LAS unsigned char* Vs = Ks + KBUF;
;                 { LAS unsigned char* kd = Ks + srow * KS_STRIDE + ssub * 16; LAS unsigned char* vd = Vs + srow * VS_STRIDE + ssub * 16;
;                   *(LAS u32x4*)(kd) = kreg[0]; *(LAS u32x4*)(kd + 128) = kreg[1]; *(LAS u32x4*)(kd + 256) = kreg[2]; *(LAS u32x4*)(vd) = vreg[0]; *(LAS u32x4*)(vd + 128) = vreg[1]; }
;                 __syncthreads();
;                 if (jt + 1 < ntiles) LOAD_TILE(jt + 1);
.LBB0_637:
	s_and_b64 s[42:43], s[44:45], exec
	s_cselect_b32 s50, s48, s49
	s_lshl_b32 s52, s50, 8
	v_add_u32_e32 v228, s52, v235
	v_ashrrev_i32_e32 v229, 31, v228
	v_lshl_add_u64 v[0:1], s[14:15], 0, v[228:229]
	v_lshlrev_b64 v[226:227], 11, v[0:1]
	v_lshl_add_u64 v[2:3], v[206:207], 0, v[226:227]
	global_load_dwordx4 v[96:99], v[2:3], off
	global_load_dwordx4 v[100:103], v[2:3], off offset:32
	global_load_dwordx4 v[104:107], v[2:3], off offset:64
	global_load_dwordx4 v[108:111], v[2:3], off offset:96
	global_load_dwordx4 v[112:115], v[2:3], off offset:128
	global_load_dwordx4 v[116:119], v[2:3], off offset:160
	global_load_dwordx4 v[120:123], v[2:3], off offset:192
	global_load_dwordx4 v[124:127], v[2:3], off offset:224
	v_lshlrev_b64 v[0:1], 10, v[0:1]
	v_lshl_add_u64 v[0:1], v[208:209], 0, v[0:1]
	global_load_dwordx4 v[128:131], v[0:1], off
	global_load_dwordx4 v[132:135], v[0:1], off offset:32
	global_load_dwordx4 v[136:139], v[0:1], off offset:64
	global_load_dwordx4 v[140:143], v[0:1], off offset:96
	s_waitcnt vmcnt(29)
	v_mov_b32_e32 v0, 0
	v_mov_b32_e32 v1, 0
	v_mov_b32_e32 v2, 0
	v_mov_b32_e32 v3, 0
	v_mov_b32_e32 v4, 0
	v_mov_b32_e32 v5, 0
	v_mov_b32_e32 v6, 0
	v_mov_b32_e32 v7, 0
	v_mov_b32_e32 v8, 0
	v_mov_b32_e32 v9, 0
	v_mov_b32_e32 v10, 0
	v_mov_b32_e32 v11, 0
	v_mov_b32_e32 v12, 0
	v_mov_b32_e32 v13, 0
	v_mov_b32_e32 v14, 0
	v_mov_b32_e32 v15, 0
	v_mov_b32_e32 v16, 0
	v_mov_b32_e32 v17, 0
	v_mov_b32_e32 v18, 0
	v_mov_b32_e32 v19, 0
	s_and_saveexec_b64 s[42:43], s[0:1]
	s_cbranch_execz .LBB0_639
	global_load_dwordx4 v[8:11], v[212:213], off
	global_load_dwordx4 v[16:19], v[198:199], off
	global_load_dwordx4 v[12:15], v[212:213], off offset:128
	global_load_dwordx4 v[0:3], v[214:215], off
	global_load_dwordx4 v[4:7], v[214:215], off offset:128
.LBB0_639:
	s_or_b64 exec, exec, s[42:43]
	v_add_u32_e32 v20, v200, v190
	s_waitcnt vmcnt(28)
	s_waitcnt vmcnt(4)
	ds_write_b128 v20, v[8:11]
	s_waitcnt vmcnt(2)
	ds_write_b128 v20, v[12:15] offset:128
	ds_write_b128 v20, v[16:19] offset:256
	s_waitcnt vmcnt(1)
	ds_write_b128 v191, v[0:3] offset:25600
	s_waitcnt vmcnt(0)
	ds_write_b128 v191, v[4:7] offset:25728
	s_waitcnt lgkmcnt(0)
	s_barrier
	s_and_saveexec_b64 s[42:43], s[4:5]
	s_cbranch_execz .LBB0_641
	global_load_dwordx4 v[148:151], v[216:217], off
	global_load_dwordx4 v[152:155], v[216:217], off offset:128
	global_load_dwordx4 v[156:159], v[218:219], off
	global_load_dwordx4 v[144:147], v[220:221], off
	global_load_dwordx4 v[160:163], v[220:221], off offset:128

; #define LAS __attribute__((address_space(3)))
; __device__ __forceinline__ void attn_phase(const Params& p, LAS unsigned char* lds) {
;     ...
;                 LAS unsigned char* Ks = lds + (jt & 1) * ABUF; LAS unsigned char* Vs = Ks + KBUF;
;                 { LAS unsigned char* kd = Ks + srow * KS_STRIDE + ssub * 16; LAS unsigned char* vd = Vs + srow * VS_STRIDE + ssub * 16;
;                   *(LAS u32x4*)(kd) = kreg[0]; *(LAS u32x4*)(kd + 128) = kreg[1]; *(LAS u32x4*)(kd + 256) = kreg[2]; *(LAS u32x4*)(vd) = vreg[0]; *(LAS u32x4*)(vd + 128) = vreg[1]; }
;                 __syncthreads();
;                 if (jt + 1 < ntiles) LOAD_TILE(jt + 1);
.LBB0_642:
	s_add_i32 s54, s8, -1
	s_bitcmp1_b32 s54, 0
	s_cselect_b32 s16, 0xb400, 0
	s_add_i32 s55, s16, 0
	v_add3_u32 v64, s55, v185, v190
	s_cmp_ge_u32 s8, s51
	v_add3_u32 v65, s55, v236, v190
	s_waitcnt vmcnt(0)
	ds_write_b128 v64, v[148:151]
	ds_write_b128 v64, v[152:155] offset:128
	ds_write_b128 v64, v[156:159] offset:256
	ds_write_b128 v65, v[144:147] offset:25600
	ds_write_b128 v65, v[160:163] offset:25728
	s_waitcnt lgkmcnt(0)
	s_barrier
	s_cbranch_scc1 .LBB0_646
	s_and_saveexec_b64 s[44:45], s[4:5]
	s_cbranch_execz .LBB0_645
	v_lshl_add_u64 v[64:65], s[28:29], 0, v[230:231]
	v_add_co_u32_e32 v66, vcc, 0x3020000, v64
	s_nop 1
	v_addc_co_u32_e32 v67, vcc, 0, v65, vcc
	global_load_dwordx4 v[148:151], v[66:67], off
	global_load_dwordx4 v[152:155], v[66:67], off offset:128
	v_lshl_add_u64 v[66:67], s[28:29], 0, v[232:233]
	v_add_co_u32_e32 v64, vcc, 0x2b520000, v64
	s_nop 1
	v_addc_co_u32_e32 v65, vcc, 0, v65, vcc
	global_load_dwordx4 v[156:159], v[66:67], off
	global_load_dwordx4 v[144:147], v[64:65], off
	global_load_dwordx4 v[160:163], v[64:65], off offset:128

; __device__ __forceinline__ unsigned cvtpk(float lo, float hi) { return pg8::cvt_pk_bf16(lo, hi); }
; __device__ __forceinline__ s16x4 vtr(const LAS unsigned char* ptr) { return __builtin_bit_cast(s16x4, __builtin_amdgcn_ds_read_tr16_b64_v4i16((LAS v4i16_t*)ptr)); }
; __device__ __forceinline__ void attn_phase(const Params& p, LAS unsigned char* lds) {
;     ...
;                 float ps = 0.f;
; #pragma unroll
;                 for (int r = 0; r < 16; ++r) { p0[r] = __builtin_amdgcn_exp2f(p0[r] - mn); p1[r] = __builtin_amdgcn_exp2f(p1[r] - mn); ps += p0[r] + p1[r]; }
;                 lrun = lrun * alpha + ps;
;                 if (__any(alpha != 1.0f)) {
; #pragma unroll
;                     for (int d = 0; d < 4; ++d) o[d] *= alpha; }
;                 bf16x8 pf[4];
; #pragma unroll
;                 for (int s = 0; s < 2; ++s) {
;                     u32x4 w0 = {cvtpk(p0[8 * s + 0], p0[8 * s + 1]), cvtpk(p0[8 * s + 2], p0[8 * s + 3]), cvtpk(p0[8 * s + 4], p0[8 * s + 5]), cvtpk(p0[8 * s + 6], p0[8 * s + 7])};
;                     u32x4 w1 = {cvtpk(p1[8 * s + 0], p1[8 * s + 1]), cvtpk(p1[8 * s + 2], p1[8 * s + 3]), cvtpk(p1[8 * s + 4], p1[8 * s + 5]), cvtpk(p1[8 * s + 6], p1[8 * s + 7])};
;                     pf[s] = __builtin_bit_cast(bf16x8, w0); pf[2 + s] = __builtin_bit_cast(bf16x8, w1); }
; #pragma unroll
;                 for (int d = 0; d < 4; ++d) {
;                     if (d < 3) {
; #pragma unroll
;                         for (int s = 0; s < 4; ++s) { vlo[(d + 1) & 1][s] = vtr(vb + (16 * s) * VS_STRIDE + (d + 1) * 64); vhi[(d + 1) & 1][s] = vtr(vb + (16 * s + 8) * VS_STRIDE + (d + 1) * 64); } }
; #pragma unroll
;                     for (int s = 0; s < 4; ++s) {
;                         const s16x4 lo = vlo[d & 1][s], hh = vhi[d & 1][s];
;                         const bf16x8 vf = {lo[0], lo[1], lo[2], lo[3], hh[0], hh[1], hh[2], hh[3]};
;                         o[d] = __builtin_amdgcn_mfma_f32_32x32x16_bf16(vf, pf[s], o[d], 0, 0, 0); } }
.LBB0_650:
	v_sub_f32_e32 v64, v64, v246
	v_sub_f32_e32 v80, v80, v246
	v_exp_f32_e32 v64, v64
	v_exp_f32_e32 v80, v80
	v_sub_f32_e32 v65, v65, v246
	v_sub_f32_e32 v81, v81, v246
	v_exp_f32_e32 v65, v65
	v_exp_f32_e32 v81, v81
	v_sub_f32_e32 v66, v66, v246
	v_sub_f32_e32 v82, v82, v246
	v_exp_f32_e32 v66, v66
	v_exp_f32_e32 v82, v82
	v_sub_f32_e32 v67, v67, v246
	v_sub_f32_e32 v83, v83, v246
	v_exp_f32_e32 v67, v67
	v_exp_f32_e32 v83, v83
	v_add_f32_e32 v248, v64, v80
	v_add_f32_e32 v249, v65, v81
	v_add_f32_e32 v248, v249, v248
	v_add_f32_e32 v249, v66, v82
	v_add_f32_e32 v248, v249, v248
	v_add_f32_e32 v249, v67, v83
	v_sub_f32_e32 v68, v68, v246
	v_sub_f32_e32 v84, v84, v246
	v_add_f32_e32 v248, v249, v248
	v_exp_f32_e32 v68, v68
	v_exp_f32_e32 v249, v84
	v_sub_f32_e32 v69, v69, v246
	v_sub_f32_e32 v85, v85, v246
	v_exp_f32_e32 v69, v69
	v_exp_f32_e32 v85, v85
	v_sub_f32_e32 v70, v70, v246
	v_sub_f32_e32 v86, v86, v246
	v_exp_f32_e32 v70, v70
	v_exp_f32_e32 v86, v86
	v_sub_f32_e32 v71, v71, v246
	v_sub_f32_e32 v87, v87, v246
	v_exp_f32_e32 v71, v71
	v_exp_f32_e32 v87, v87
	v_sub_f32_e32 v72, v72, v246
	v_sub_f32_e32 v88, v88, v246
	v_add_f32_e32 v84, v68, v249
	v_exp_f32_e32 v72, v72
	v_exp_f32_e32 v88, v88
	v_sub_f32_e32 v73, v73, v246
	v_sub_f32_e32 v89, v89, v246
	v_add_f32_e32 v84, v84, v248
	v_add_f32_e32 v248, v69, v85
	v_exp_f32_e32 v73, v73
	v_exp_f32_e32 v89, v89
	v_sub_f32_e32 v74, v74, v246
	v_sub_f32_e32 v90, v90, v246
	v_add_f32_e32 v84, v248, v84
	v_add_f32_e32 v248, v70, v86
	v_exp_f32_e32 v74, v74
	v_exp_f32_e32 v90, v90
	v_sub_f32_e32 v75, v75, v246
	v_sub_f32_e32 v91, v91, v246
	v_add_f32_e32 v84, v248, v84
	v_add_f32_e32 v248, v71, v87
	v_exp_f32_e32 v75, v75
	v_exp_f32_e32 v91, v91
	v_add_f32_e32 v84, v248, v84
	v_add_f32_e32 v248, v72, v88
	v_add_f32_e32 v84, v248, v84
	v_add_f32_e32 v248, v73, v89
	v_add_f32_e32 v84, v248, v84
	v_add_f32_e32 v248, v74, v90
	v_add_f32_e32 v84, v248, v84
	v_add_f32_e32 v248, v75, v91
	v_sub_f32_e32 v76, v76, v246
	v_add_f32_e32 v84, v248, v84
	v_exp_f32_e32 v248, v76
	v_sub_f32_e32 v76, v92, v246
	v_sub_f32_e32 v77, v77, v246
	v_exp_f32_e32 v92, v76
	v_exp_f32_e32 v250, v77
	v_sub_f32_e32 v77, v93, v246
	v_exp_f32_e32 v93, v77
	v_add_f32_e32 v76, v248, v92
	v_add_f32_e32 v76, v76, v84
	v_cvt_pk_bf16_f32 v72, v72, v73
	v_add_f32_e32 v77, v250, v93
	v_add_f32_e32 v76, v77, v76
	v_sub_f32_e32 v77, v78, v246
	v_exp_f32_e32 v251, v77
	v_sub_f32_e32 v77, v94, v246
	v_exp_f32_e32 v94, v77
	v_cvt_pk_bf16_f32 v78, v68, v69
	v_cvt_pk_bf16_f32 v68, v80, v81
	v_cvt_pk_bf16_f32 v69, v82, v83
	v_add_f32_e32 v77, v251, v94
	v_add_f32_e32 v76, v77, v76
	v_sub_f32_e32 v77, v79, v246
	v_exp_f32_e32 v252, v77
	v_sub_f32_e32 v77, v95, v246
	v_exp_f32_e32 v95, v77
	v_cvt_pk_bf16_f32 v79, v70, v71
	v_cvt_pk_bf16_f32 v70, v249, v85
	v_cvt_pk_bf16_f32 v71, v86, v87
	v_add_f32_e32 v77, v252, v95
	v_add_f32_e32 v84, v77, v76
	v_cvt_pk_bf16_f32 v76, v64, v65
	v_cvt_pk_bf16_f32 v77, v66, v67
	v_cvt_pk_bf16_f32 v73, v74, v75
	v_cvt_pk_bf16_f32 v74, v248, v250
	v_cvt_pk_bf16_f32 v75, v251, v252
	v_cvt_pk_bf16_f32 v64, v88, v89
	v_cvt_pk_bf16_f32 v65, v90, v91
	v_cvt_pk_bf16_f32 v66, v92, v93
	ds_read_b64_tr_b16 v[80:81], v247 offset:25664
	ds_read_b64_tr_b16 v[82:83], v247 offset:28224
	ds_read_b64_tr_b16 v[86:87], v247 offset:30784
	ds_read_b64_tr_b16 v[88:89], v247 offset:33344
	ds_read_b64_tr_b16 v[90:91], v247 offset:35904
	ds_read_b64_tr_b16 v[92:93], v247 offset:38464
	ds_read_b64_tr_b16 v[248:249], v247 offset:41024
	ds_read_b64_tr_b16 v[250:251], v247 offset:43584
	v_mfma_f32_32x32x16_bf16 v[48:63], v[176:179], v[76:79], v[48:63]
	v_cvt_pk_bf16_f32 v67, v94, v95
	s_add_i32 s53, s53, 64
	s_add_i32 s8, s8, 1
	v_fmac_f32_e32 v84, v229, v182
	v_lshl_add_u64 v[232:233], v[232:233], 0, s[10:11]
	v_lshl_add_u64 v[230:231], v[230:231], 0, s[12:13]
	s_cmp_eq_u32 s52, s53
	s_waitcnt lgkmcnt(6)
	v_mfma_f32_32x32x16_bf16 v[32:47], v[80:83], v[76:79], v[32:47]
	v_mfma_f32_32x32x16_bf16 v[48:63], v[172:175], v[72:75], v[48:63]
	s_waitcnt lgkmcnt(4)
	v_mfma_f32_32x32x16_bf16 v[32:47], v[86:89], v[72:75], v[32:47]
	v_mfma_f32_32x32x16_bf16 v[48:63], v[168:171], v[68:71], v[48:63]
	s_waitcnt lgkmcnt(2)
	v_mfma_f32_32x32x16_bf16 v[32:47], v[90:93], v[68:71], v[32:47]
	v_mfma_f32_32x32x16_bf16 v[48:63], v[164:167], v[64:67], v[48:63]
	ds_read_b64_tr_b16 v[164:165], v247 offset:25728
	ds_read_b64_tr_b16 v[166:167], v247 offset:28288
	ds_read_b64_tr_b16 v[168:169], v247 offset:30848
	ds_read_b64_tr_b16 v[170:171], v247 offset:33408
	ds_read_b64_tr_b16 v[172:173], v247 offset:35968
	ds_read_b64_tr_b16 v[174:175], v247 offset:38528
	ds_read_b64_tr_b16 v[176:177], v247 offset:41088
	ds_read_b64_tr_b16 v[178:179], v247 offset:43648
	s_waitcnt lgkmcnt(8)
	v_mfma_f32_32x32x16_bf16 v[32:47], v[248:251], v[64:67], v[32:47]
	ds_read_b64_tr_b16 v[86:87], v247 offset:25792
	ds_read_b64_tr_b16 v[88:89], v247 offset:28352
	ds_read_b64_tr_b16 v[90:91], v247 offset:30912
	ds_read_b64_tr_b16 v[92:93], v247 offset:33472
	ds_read_b64_tr_b16 v[248:249], v247 offset:36032
	ds_read_b64_tr_b16 v[250:251], v247 offset:38592
	ds_read_b64_tr_b16 v[80:81], v247 offset:41152
	ds_read_b64_tr_b16 v[82:83], v247 offset:43712
	s_waitcnt lgkmcnt(14)
	v_mfma_f32_32x32x16_bf16 v[16:31], v[164:167], v[76:79], v[16:31]
	s_waitcnt lgkmcnt(6)
	v_mfma_f32_32x32x16_bf16 v[0:15], v[86:89], v[76:79], v[0:15]
	v_mfma_f32_32x32x16_bf16 v[16:31], v[168:171], v[72:75], v[16:31]
	s_waitcnt lgkmcnt(4)
	v_mfma_f32_32x32x16_bf16 v[0:15], v[90:93], v[72:75], v[0:15]
	v_mfma_f32_32x32x16_bf16 v[16:31], v[172:175], v[68:71], v[16:31]
	s_waitcnt lgkmcnt(2)
	v_mfma_f32_32x32x16_bf16 v[0:15], v[248:251], v[68:71], v[0:15]
	v_mfma_f32_32x32x16_bf16 v[16:31], v[176:179], v[64:67], v[16:31]
	s_waitcnt lgkmcnt(0)
	v_mfma_f32_32x32x16_bf16 v[0:15], v[80:83], v[64:67], v[0:15]
	s_cbranch_scc1 .LBB0_636
	v_mov_b32_e32 v229, v84
	v_mov_b32_e32 v182, v246
	s_branch .LBB0_642
